# phase C chunk-record stores (read much later by other CUs) marked nt so they do not push the prefetched projection rows and conv weights out of the XCD L2
# speedup vs baseline: 1.0140x; 1.0029x over previous
; #define LAS __attribute__((address_space(3)))
; __device__ __forceinline__ unsigned cvtpk(float lo, float hi) { const f32x2_t v = {lo, hi}; const bf16x2_t b = __builtin_convertvector(v, bf16x2_t); return __builtin_bit_cast(unsigned, b); }
; __device__ __forceinline__ void gdn_prep_unit(LAS unsigned char* lds, unsigned char* ws, const float* conv_w, const float* a_log, const float* dt_bias,
;                                               int l, int Tp, int ci, int h, int nci, int nh, unsigned& pre_ba, int tid, int wave, int lane) {
;     ...
;             if (mat == 0) {
;                 v4u o; o.x = cvtpk(y[0], y[1]); o.y = cvtpk(y[2], y[3]); o.z = cvtpk(y[4], y[5]); o.w = cvtpk(y[6], y[7]);
;                 *(LAS v4u*)(lds + D1_QROW + c * ROWP + ch0 * 2) = o;
;                 const int t = ch0 >> 5, kk = ch0 & 31, s = kk >> 4, b = (kk >> 3) & 1;
; #pragma unroll
;                 for (int d = 0; d < 2; ++d) { const int r = d ? 63 - c : c; const float e = __expf(GC[d * 64 + r]); const int i = r >> 5, rr = r & 31;
;                     unsigned char* fb = gdn_rec(ws, d, ci, h) + REC_FQ + (((i * 4 + t) * 2 + s) * 64) * 16 + b * 8;
;                     v2u lo, hi2; lo.x = cvtpk(y[0] * e, y[1] * e); lo.y = cvtpk(y[2] * e, y[3] * e); hi2.x = cvtpk(y[4] * e, y[5] * e); hi2.y = cvtpk(y[6] * e, y[7] * e);
;                     *(v2u*)(fb + rr * 16) = lo; *(v2u*)(fb + (rr + 32) * 16) = hi2; }
.LBB0_338:
	s_or_saveexec_b64 vcc, s[90:91]
	s_ashr_i32 s81, s80, 31
	s_lshl_b64 s[80:81], s[80:81], 3
	s_or_b32 s7, s80, s7
	v_add_u32_e32 v34, v110, v115
	s_mul_i32 s80, s81, 0x12000
	s_mul_hi_u32 s16, s7, 0x12000
	s_mul_i32 s17, s7, 0x12000
	s_xor_b64 exec, exec, vcc
	s_cbranch_execz .LBB0_340
	v_cvt_pk_bf16_f32 v12, v32, v33
	v_cvt_pk_bf16_f32 v13, v6, v7
	v_cvt_pk_bf16_f32 v14, v10, v11
	v_cvt_pk_bf16_f32 v15, v8, v9
	ds_write_b128 v34, v[12:15]
	ds_read_b32 v12, v116
	s_add_i32 s4, s16, s80
	s_add_u32 s90, s42, s17
	s_addc_u32 s91, s43, s4
	v_lshl_add_u64 v[14:15], s[90:91], 0, v[40:41]
	s_waitcnt lgkmcnt(0)
	v_mul_f32_e32 v12, 0x3fb8aa3b, v12
	v_exp_f32_e32 v12, v12
	v_lshl_add_u64 v[14:15], v[14:15], 0, v[38:39]
	s_mov_b64 s[4:5], 0x4d604000
	v_lshl_add_u64 v[14:15], v[14:15], 0, s[4:5]
	v_pk_mul_f32 v[16:17], v[32:33], v[12:13] op_sel_hi:[1,0]
	v_pk_mul_f32 v[18:19], v[6:7], v[12:13] op_sel_hi:[1,0]
	v_cvt_pk_bf16_f32 v16, v16, v17
	v_cvt_pk_bf16_f32 v17, v18, v19
	v_pk_mul_f32 v[18:19], v[10:11], v[12:13] op_sel_hi:[1,0]
	v_pk_mul_f32 v[12:13], v[8:9], v[12:13] op_sel_hi:[1,0]
	v_cvt_pk_bf16_f32 v18, v18, v19
	v_cvt_pk_bf16_f32 v19, v12, v13
	v_lshl_add_u64 v[12:13], v[14:15], 0, v[44:45]
	global_store_dwordx2 v[12:13], v[16:17], off nt
	v_lshl_add_u64 v[12:13], v[14:15], 0, v[42:43]
	global_store_dwordx2 v[12:13], v[18:19], off offset:512 nt
	ds_read_b32 v12, v117
	v_lshl_add_u64 v[14:15], s[90:91], 0, v[46:47]
	v_lshl_add_u64 v[14:15], v[14:15], 0, v[38:39]
	s_mov_b64 s[4:5], 0x56604000
	v_lshl_add_u64 v[14:15], v[14:15], 0, s[4:5]
	s_waitcnt lgkmcnt(0)
	v_mul_f32_e32 v12, 0x3fb8aa3b, v12
	v_exp_f32_e32 v12, v12
	s_nop 0
	v_pk_mul_f32 v[16:17], v[32:33], v[12:13] op_sel_hi:[1,0]
	v_pk_mul_f32 v[6:7], v[6:7], v[12:13] op_sel_hi:[1,0]
	v_cvt_pk_bf16_f32 v16, v16, v17
	v_cvt_pk_bf16_f32 v17, v6, v7
	v_pk_mul_f32 v[6:7], v[10:11], v[12:13] op_sel_hi:[1,0]
	v_pk_mul_f32 v[8:9], v[8:9], v[12:13] op_sel_hi:[1,0]
	v_cvt_pk_bf16_f32 v6, v6, v7
	v_cvt_pk_bf16_f32 v7, v8, v9
	v_lshl_add_u64 v[8:9], v[14:15], 0, v[48:49]
	global_store_dwordx2 v[8:9], v[16:17], off nt
	v_lshl_add_u64 v[8:9], v[14:15], 0, v[50:51]
	global_store_dwordx2 v[8:9], v[6:7], off nt

; #define LAS __attribute__((address_space(3)))
; __device__ __forceinline__ unsigned cvtpk(float lo, float hi) { const f32x2_t v = {lo, hi}; const bf16x2_t b = __builtin_convertvector(v, bf16x2_t); return __builtin_bit_cast(unsigned, b); }
; __device__ __forceinline__ void gdn_prep_unit(LAS unsigned char* lds, unsigned char* ws, const float* conv_w, const float* a_log, const float* dt_bias,
;                                               int l, int Tp, int ci, int h, int nci, int nh, unsigned& pre_ba, int tid, int wave, int lane) {
;     ...
;             if (mat == 0) {
;                 v4u o; o.x = cvtpk(y[0], y[1]); o.y = cvtpk(y[2], y[3]); o.z = cvtpk(y[4], y[5]); o.w = cvtpk(y[6], y[7]);
;                 *(LAS v4u*)(lds + D1_QROW + c * ROWP + ch0 * 2) = o;
;                 const int t = ch0 >> 5, kk = ch0 & 31, s = kk >> 4, b = (kk >> 3) & 1;
; #pragma unroll
;                 for (int d = 0; d < 2; ++d) { const int r = d ? 63 - c : c; const float e = __expf(GC[d * 64 + r]); const int i = r >> 5, rr = r & 31;
;                     unsigned char* fb = gdn_rec(ws, d, ci, h) + REC_FQ + (((i * 4 + t) * 2 + s) * 64) * 16 + b * 8;
;                     v2u lo, hi2; lo.x = cvtpk(y[0] * e, y[1] * e); lo.y = cvtpk(y[2] * e, y[3] * e); hi2.x = cvtpk(y[4] * e, y[5] * e); hi2.y = cvtpk(y[6] * e, y[7] * e);
;                     *(v2u*)(fb + rr * 16) = lo; *(v2u*)(fb + (rr + 32) * 16) = hi2; }
.LBB0_352:
	s_andn2_saveexec_b64 vcc, s[90:91]
	s_cbranch_execz .LBB0_354
	v_cvt_pk_bf16_f32 v12, v32, v33
	v_cvt_pk_bf16_f32 v13, v6, v7
	v_cvt_pk_bf16_f32 v14, v10, v11
	v_cvt_pk_bf16_f32 v15, v8, v9
	v_add_u32_e32 v16, v110, v120
	ds_write_b128 v16, v[12:15]
	ds_read_b32 v12, v121
	s_add_i32 s4, s16, s80
	s_add_u32 s90, s42, s17
	s_addc_u32 s91, s43, s4
	v_lshl_add_u64 v[14:15], s[90:91], 0, v[52:53]
	s_waitcnt lgkmcnt(0)
	v_mul_f32_e32 v12, 0x3fb8aa3b, v12
	v_exp_f32_e32 v12, v12
	v_lshl_add_u64 v[14:15], v[14:15], 0, v[38:39]
	s_mov_b64 s[4:5], 0x4d604000
	v_lshl_add_u64 v[14:15], v[14:15], 0, s[4:5]
	v_pk_mul_f32 v[16:17], v[32:33], v[12:13] op_sel_hi:[1,0]
	v_pk_mul_f32 v[18:19], v[6:7], v[12:13] op_sel_hi:[1,0]
	v_cvt_pk_bf16_f32 v16, v16, v17
	v_cvt_pk_bf16_f32 v17, v18, v19
	v_pk_mul_f32 v[18:19], v[10:11], v[12:13] op_sel_hi:[1,0]
	v_pk_mul_f32 v[12:13], v[8:9], v[12:13] op_sel_hi:[1,0]
	v_cvt_pk_bf16_f32 v18, v18, v19
	v_cvt_pk_bf16_f32 v19, v12, v13
	v_lshl_add_u64 v[12:13], v[14:15], 0, v[54:55]
	global_store_dwordx2 v[12:13], v[16:17], off nt
	v_lshl_add_u64 v[12:13], v[14:15], 0, v[56:57]
	global_store_dwordx2 v[12:13], v[18:19], off nt
	ds_read_b32 v12, v122
	v_lshl_add_u64 v[14:15], s[90:91], 0, v[58:59]
	v_lshl_add_u64 v[14:15], v[14:15], 0, v[38:39]
	s_mov_b64 s[4:5], 0x56604000
	v_lshl_add_u64 v[14:15], v[14:15], 0, s[4:5]
	s_waitcnt lgkmcnt(0)
	v_mul_f32_e32 v12, 0x3fb8aa3b, v12
	v_exp_f32_e32 v12, v12
	s_nop 0
	v_pk_mul_f32 v[16:17], v[32:33], v[12:13] op_sel_hi:[1,0]
	v_pk_mul_f32 v[6:7], v[6:7], v[12:13] op_sel_hi:[1,0]
	v_cvt_pk_bf16_f32 v16, v16, v17
	v_cvt_pk_bf16_f32 v17, v6, v7
	v_pk_mul_f32 v[6:7], v[10:11], v[12:13] op_sel_hi:[1,0]
	v_pk_mul_f32 v[8:9], v[8:9], v[12:13] op_sel_hi:[1,0]
	v_cvt_pk_bf16_f32 v6, v6, v7
	v_cvt_pk_bf16_f32 v7, v8, v9
	v_lshl_add_u64 v[8:9], v[14:15], 0, v[60:61]
	global_store_dwordx2 v[8:9], v[16:17], off nt
	v_lshl_add_u64 v[8:9], v[14:15], 0, v[62:63]
	global_store_dwordx2 v[8:9], v[6:7], off nt

; #define LAS __attribute__((address_space(3)))
; __device__ __forceinline__ unsigned cvtpk(float lo, float hi) { const f32x2_t v = {lo, hi}; const bf16x2_t b = __builtin_convertvector(v, bf16x2_t); return __builtin_bit_cast(unsigned, b); }
; __device__ __forceinline__ void gdn_prep_unit(LAS unsigned char* lds, unsigned char* ws, const float* conv_w, const float* a_log, const float* dt_bias,
;                                               int l, int Tp, int ci, int h, int nci, int nh, unsigned& pre_ba, int tid, int wave, int lane) {
;     ...
;                 v4u o; o.x = cvtpk(y[0], y[1]); o.y = cvtpk(y[2], y[3]); o.z = cvtpk(y[4], y[5]); o.w = cvtpk(y[6], y[7]);
;                 *(LAS v4u*)(lds + D1_QROW + c * ROWP + ch0 * 2) = o;
;                 const int t = ch0 >> 5, kk = ch0 & 31, s = kk >> 4, b = (kk >> 3) & 1;
; #pragma unroll
;                 for (int d = 0; d < 2; ++d) { const int r = d ? 63 - c : c; const float e = __expf(GC[d * 64 + r]); const int i = r >> 5, rr = r & 31;
;                     unsigned char* fb = gdn_rec(ws, d, ci, h) + REC_FQ + (((i * 4 + t) * 2 + s) * 64) * 16 + b * 8;
;                     v2u lo, hi2; lo.x = cvtpk(y[0] * e, y[1] * e); lo.y = cvtpk(y[2] * e, y[3] * e); hi2.x = cvtpk(y[4] * e, y[5] * e); hi2.y = cvtpk(y[6] * e, y[7] * e);
;                     *(v2u*)(fb + rr * 16) = lo; *(v2u*)(fb + (rr + 32) * 16) = hi2; }
.LBB0_366:
	s_andn2_saveexec_b64 vcc, s[90:91]
	s_cbranch_execz .LBB0_368
	v_cvt_pk_bf16_f32 v12, v32, v33
	v_cvt_pk_bf16_f32 v13, v6, v7
	v_cvt_pk_bf16_f32 v14, v10, v11
	v_cvt_pk_bf16_f32 v15, v8, v9
	ds_write_b128 v34, v[12:15]
	ds_read_b32 v12, v116
	s_add_i32 s4, s16, s80
	s_add_u32 s90, s42, s17
	s_addc_u32 s91, s43, s4
	v_lshl_add_u64 v[14:15], s[90:91], 0, v[40:41]
	s_waitcnt lgkmcnt(0)
	v_mul_f32_e32 v12, 0x3fb8aa3b, v12
	v_exp_f32_e32 v12, v12
	v_lshl_add_u64 v[14:15], v[14:15], 0, v[38:39]
	s_mov_b64 s[4:5], 0x4d604000
	v_lshl_add_u64 v[14:15], v[14:15], 0, s[4:5]
	v_pk_mul_f32 v[16:17], v[32:33], v[12:13] op_sel_hi:[1,0]
	v_pk_mul_f32 v[18:19], v[6:7], v[12:13] op_sel_hi:[1,0]
	v_cvt_pk_bf16_f32 v16, v16, v17
	v_cvt_pk_bf16_f32 v17, v18, v19
	v_pk_mul_f32 v[18:19], v[10:11], v[12:13] op_sel_hi:[1,0]
	v_pk_mul_f32 v[12:13], v[8:9], v[12:13] op_sel_hi:[1,0]
	v_cvt_pk_bf16_f32 v18, v18, v19
	v_cvt_pk_bf16_f32 v19, v12, v13
	v_lshl_add_u64 v[12:13], v[14:15], 0, v[64:65]
	global_store_dwordx2 v[12:13], v[16:17], off nt
	v_lshl_add_u64 v[12:13], v[14:15], 0, v[66:67]
	global_store_dwordx2 v[12:13], v[18:19], off nt
	ds_read_b32 v12, v124
	v_lshl_add_u64 v[14:15], s[90:91], 0, v[68:69]
	v_lshl_add_u64 v[14:15], v[14:15], 0, v[38:39]
	s_mov_b64 s[4:5], 0x56604000
	v_lshl_add_u64 v[14:15], v[14:15], 0, s[4:5]
	s_waitcnt lgkmcnt(0)
	v_mul_f32_e32 v12, 0x3fb8aa3b, v12
	v_exp_f32_e32 v12, v12
	s_nop 0
	v_pk_mul_f32 v[16:17], v[32:33], v[12:13] op_sel_hi:[1,0]
	v_pk_mul_f32 v[6:7], v[6:7], v[12:13] op_sel_hi:[1,0]
	v_cvt_pk_bf16_f32 v16, v16, v17
	v_cvt_pk_bf16_f32 v17, v6, v7
	v_pk_mul_f32 v[6:7], v[10:11], v[12:13] op_sel_hi:[1,0]
	v_pk_mul_f32 v[8:9], v[8:9], v[12:13] op_sel_hi:[1,0]
	v_cvt_pk_bf16_f32 v6, v6, v7
	v_cvt_pk_bf16_f32 v7, v8, v9
	v_lshl_add_u64 v[8:9], v[14:15], 0, v[70:71]
	global_store_dwordx2 v[8:9], v[16:17], off nt
	v_lshl_add_u64 v[8:9], v[14:15], 0, v[72:73]
	global_store_dwordx2 v[8:9], v[6:7], off nt

; #define LAS __attribute__((address_space(3)))
; __device__ __forceinline__ unsigned cvtpk(float lo, float hi) { const f32x2_t v = {lo, hi}; const bf16x2_t b = __builtin_convertvector(v, bf16x2_t); return __builtin_bit_cast(unsigned, b); }
; __device__ __forceinline__ void gdn_prep_unit(LAS unsigned char* lds, unsigned char* ws, const float* conv_w, const float* a_log, const float* dt_bias,
;                                               int l, int Tp, int ci, int h, int nci, int nh, unsigned& pre_ba, int tid, int wave, int lane) {
;     ...
;                 v4u o; o.x = cvtpk(y[0], y[1]); o.y = cvtpk(y[2], y[3]); o.z = cvtpk(y[4], y[5]); o.w = cvtpk(y[6], y[7]);
;                 *(LAS v4u*)(lds + D1_QROW + c * ROWP + ch0 * 2) = o;
;                 const int t = ch0 >> 5, kk = ch0 & 31, s = kk >> 4, b = (kk >> 3) & 1;
; #pragma unroll
;                 for (int d = 0; d < 2; ++d) { const int r = d ? 63 - c : c; const float e = __expf(GC[d * 64 + r]); const int i = r >> 5, rr = r & 31;
;                     unsigned char* fb = gdn_rec(ws, d, ci, h) + REC_FQ + (((i * 4 + t) * 2 + s) * 64) * 16 + b * 8;
;                     v2u lo, hi2; lo.x = cvtpk(y[0] * e, y[1] * e); lo.y = cvtpk(y[2] * e, y[3] * e); hi2.x = cvtpk(y[4] * e, y[5] * e); hi2.y = cvtpk(y[6] * e, y[7] * e);
;                     *(v2u*)(fb + rr * 16) = lo; *(v2u*)(fb + (rr + 32) * 16) = hi2; }
.LBB0_380:
	s_andn2_saveexec_b64 vcc, s[90:91]
	s_cbranch_execz .LBB0_382
	v_cvt_pk_bf16_f32 v12, v32, v33
	v_cvt_pk_bf16_f32 v13, v6, v7
	v_cvt_pk_bf16_f32 v14, v10, v11
	v_cvt_pk_bf16_f32 v15, v8, v9
	v_add_u32_e32 v16, v110, v127
	ds_write_b128 v16, v[12:15]
	ds_read_b32 v12, v128
	s_add_i32 s4, s16, s80
	s_add_u32 s90, s42, s17
	s_addc_u32 s91, s43, s4
	v_lshl_add_u64 v[14:15], s[90:91], 0, v[74:75]
	s_waitcnt lgkmcnt(0)
	v_mul_f32_e32 v12, 0x3fb8aa3b, v12
	v_exp_f32_e32 v12, v12
	v_lshl_add_u64 v[14:15], v[14:15], 0, v[38:39]
	s_mov_b64 s[4:5], 0x4d604000
	v_lshl_add_u64 v[14:15], v[14:15], 0, s[4:5]
	v_pk_mul_f32 v[16:17], v[32:33], v[12:13] op_sel_hi:[1,0]
	v_pk_mul_f32 v[18:19], v[6:7], v[12:13] op_sel_hi:[1,0]
	v_cvt_pk_bf16_f32 v16, v16, v17
	v_cvt_pk_bf16_f32 v17, v18, v19
	v_pk_mul_f32 v[18:19], v[10:11], v[12:13] op_sel_hi:[1,0]
	v_pk_mul_f32 v[12:13], v[8:9], v[12:13] op_sel_hi:[1,0]
	v_cvt_pk_bf16_f32 v18, v18, v19
	v_cvt_pk_bf16_f32 v19, v12, v13
	v_lshl_add_u64 v[12:13], v[14:15], 0, v[76:77]
	global_store_dwordx2 v[12:13], v[16:17], off nt
	v_lshl_add_u64 v[12:13], v[14:15], 0, v[78:79]
	global_store_dwordx2 v[12:13], v[18:19], off nt
	ds_read_b32 v12, v129
	v_lshl_add_u64 v[14:15], s[90:91], 0, v[80:81]
	v_lshl_add_u64 v[14:15], v[14:15], 0, v[38:39]
	s_mov_b64 s[4:5], 0x56604000
	v_lshl_add_u64 v[14:15], v[14:15], 0, s[4:5]
	s_waitcnt lgkmcnt(0)
	v_mul_f32_e32 v12, 0x3fb8aa3b, v12
	v_exp_f32_e32 v12, v12
	s_nop 0
	v_pk_mul_f32 v[16:17], v[32:33], v[12:13] op_sel_hi:[1,0]
	v_pk_mul_f32 v[6:7], v[6:7], v[12:13] op_sel_hi:[1,0]
	v_cvt_pk_bf16_f32 v16, v16, v17
	v_cvt_pk_bf16_f32 v17, v6, v7
	v_pk_mul_f32 v[6:7], v[10:11], v[12:13] op_sel_hi:[1,0]
	v_pk_mul_f32 v[8:9], v[8:9], v[12:13] op_sel_hi:[1,0]
	v_cvt_pk_bf16_f32 v6, v6, v7
	v_cvt_pk_bf16_f32 v7, v8, v9
	v_lshl_add_u64 v[8:9], v[14:15], 0, v[82:83]
	global_store_dwordx2 v[8:9], v[16:17], off nt
	v_lshl_add_u64 v[8:9], v[14:15], 0, v[84:85]
	global_store_dwordx2 v[8:9], v[6:7], off nt

; #define LAS __attribute__((address_space(3)))
; __device__ __forceinline__ unsigned cvtpk(float lo, float hi) { const f32x2_t v = {lo, hi}; const bf16x2_t b = __builtin_convertvector(v, bf16x2_t); return __builtin_bit_cast(unsigned, b); }
; __device__ __forceinline__ void gdn_prep_unit(LAS unsigned char* lds, unsigned char* ws, const float* conv_w, const float* a_log, const float* dt_bias,
;                                               int l, int Tp, int ci, int h, int nci, int nh, unsigned& pre_ba, int tid, int wave, int lane) {
;     ...
;                 v4u o; o.x = cvtpk(y[0], y[1]); o.y = cvtpk(y[2], y[3]); o.z = cvtpk(y[4], y[5]); o.w = cvtpk(y[6], y[7]);
;                 *(LAS v4u*)(lds + D1_QROW + c * ROWP + ch0 * 2) = o;
;                 const int t = ch0 >> 5, kk = ch0 & 31, s = kk >> 4, b = (kk >> 3) & 1;
; #pragma unroll
;                 for (int d = 0; d < 2; ++d) { const int r = d ? 63 - c : c; const float e = __expf(GC[d * 64 + r]); const int i = r >> 5, rr = r & 31;
;                     unsigned char* fb = gdn_rec(ws, d, ci, h) + REC_FQ + (((i * 4 + t) * 2 + s) * 64) * 16 + b * 8;
;                     v2u lo, hi2; lo.x = cvtpk(y[0] * e, y[1] * e); lo.y = cvtpk(y[2] * e, y[3] * e); hi2.x = cvtpk(y[4] * e, y[5] * e); hi2.y = cvtpk(y[6] * e, y[7] * e);
;                     *(v2u*)(fb + rr * 16) = lo; *(v2u*)(fb + (rr + 32) * 16) = hi2; }
.LBB0_394:
	s_andn2_saveexec_b64 s[84:85], s[84:85]
	s_cbranch_execz .LBB0_396
	v_cvt_pk_bf16_f32 v12, v30, v31
	v_cvt_pk_bf16_f32 v13, v6, v7
	v_cvt_pk_bf16_f32 v14, v10, v11
	v_cvt_pk_bf16_f32 v15, v8, v9
	ds_write_b128 v34, v[12:15]
	ds_read_b32 v12, v116
	s_add_i32 s4, s16, s80
	s_add_u32 s88, s42, s17
	s_addc_u32 s89, s43, s4
	v_lshl_add_u64 v[14:15], s[88:89], 0, v[40:41]
	s_waitcnt lgkmcnt(0)
	v_mul_f32_e32 v12, 0x3fb8aa3b, v12
	v_exp_f32_e32 v12, v12
	v_lshl_add_u64 v[14:15], v[14:15], 0, v[38:39]
	s_mov_b64 s[4:5], 0x4d604000
	v_lshl_add_u64 v[14:15], v[14:15], 0, s[4:5]
	v_pk_mul_f32 v[16:17], v[30:31], v[12:13] op_sel_hi:[1,0]
	v_pk_mul_f32 v[18:19], v[6:7], v[12:13] op_sel_hi:[1,0]
	v_cvt_pk_bf16_f32 v16, v16, v17
	v_cvt_pk_bf16_f32 v17, v18, v19
	v_pk_mul_f32 v[18:19], v[10:11], v[12:13] op_sel_hi:[1,0]
	v_pk_mul_f32 v[12:13], v[8:9], v[12:13] op_sel_hi:[1,0]
	v_cvt_pk_bf16_f32 v18, v18, v19
	v_cvt_pk_bf16_f32 v19, v12, v13
	v_lshl_add_u64 v[12:13], v[14:15], 0, v[64:65]
	global_store_dwordx2 v[12:13], v[16:17], off nt
	v_lshl_add_u64 v[12:13], v[14:15], 0, v[66:67]
	global_store_dwordx2 v[12:13], v[18:19], off nt
	ds_read_b32 v12, v131
	v_lshl_add_u64 v[14:15], s[88:89], 0, v[86:87]
	v_lshl_add_u64 v[14:15], v[14:15], 0, v[38:39]
	s_mov_b64 s[4:5], 0x56604000
	v_lshl_add_u64 v[14:15], v[14:15], 0, s[4:5]
	s_waitcnt lgkmcnt(0)
	v_mul_f32_e32 v12, 0x3fb8aa3b, v12
	v_exp_f32_e32 v12, v12
	s_nop 0
	v_pk_mul_f32 v[16:17], v[30:31], v[12:13] op_sel_hi:[1,0]
	v_pk_mul_f32 v[6:7], v[6:7], v[12:13] op_sel_hi:[1,0]
	v_cvt_pk_bf16_f32 v16, v16, v17
	v_cvt_pk_bf16_f32 v17, v6, v7
	v_pk_mul_f32 v[6:7], v[10:11], v[12:13] op_sel_hi:[1,0]
	v_pk_mul_f32 v[8:9], v[8:9], v[12:13] op_sel_hi:[1,0]
	v_cvt_pk_bf16_f32 v6, v6, v7
	v_cvt_pk_bf16_f32 v7, v8, v9
	v_lshl_add_u64 v[8:9], v[14:15], 0, v[88:89]
	global_store_dwordx2 v[8:9], v[16:17], off nt
	v_lshl_add_u64 v[8:9], v[14:15], 0, v[90:91]
	global_store_dwordx2 v[8:9], v[6:7], off nt

; #define LAS __attribute__((address_space(3)))
; __device__ __forceinline__ unsigned cvtpk(float lo, float hi) { const f32x2_t v = {lo, hi}; const bf16x2_t b = __builtin_convertvector(v, bf16x2_t); return __builtin_bit_cast(unsigned, b); }
; __device__ __forceinline__ void gdn_prep_unit(LAS unsigned char* lds, unsigned char* ws, const float* conv_w, const float* a_log, const float* dt_bias,
;                                               int l, int Tp, int ci, int h, int nci, int nh, unsigned& pre_ba, int tid, int wave, int lane) {
;     ...
;                 v4u o; o.x = cvtpk(y[0], y[1]); o.y = cvtpk(y[2], y[3]); o.z = cvtpk(y[4], y[5]); o.w = cvtpk(y[6], y[7]);
;                 *(LAS v4u*)(lds + D1_QROW + c * ROWP + ch0 * 2) = o;
;                 const int t = ch0 >> 5, kk = ch0 & 31, s = kk >> 4, b = (kk >> 3) & 1;
; #pragma unroll
;                 for (int d = 0; d < 2; ++d) { const int r = d ? 63 - c : c; const float e = __expf(GC[d * 64 + r]); const int i = r >> 5, rr = r & 31;
;                     unsigned char* fb = gdn_rec(ws, d, ci, h) + REC_FQ + (((i * 4 + t) * 2 + s) * 64) * 16 + b * 8;
;                     v2u lo, hi2; lo.x = cvtpk(y[0] * e, y[1] * e); lo.y = cvtpk(y[2] * e, y[3] * e); hi2.x = cvtpk(y[4] * e, y[5] * e); hi2.y = cvtpk(y[6] * e, y[7] * e);
;                     *(v2u*)(fb + rr * 16) = lo; *(v2u*)(fb + (rr + 32) * 16) = hi2; }
.LBB0_408:
	s_andn2_saveexec_b64 s[26:27], s[26:27]
	s_cbranch_execz .LBB0_410
	v_cvt_pk_bf16_f32 v12, v30, v31
	v_cvt_pk_bf16_f32 v13, v6, v7
	v_cvt_pk_bf16_f32 v14, v10, v11
	v_cvt_pk_bf16_f32 v15, v8, v9
	v_add_u32_e32 v16, v110, v135
	ds_write_b128 v16, v[12:15]
	ds_read_b32 v12, v136
	s_add_i32 s16, s16, s80
	s_add_u32 s30, s42, s17
	s_addc_u32 s31, s43, s16
	v_lshl_add_u64 v[14:15], s[30:31], 0, v[92:93]
	s_waitcnt lgkmcnt(0)
	v_mul_f32_e32 v12, 0x3fb8aa3b, v12
	v_exp_f32_e32 v12, v12
	v_lshl_add_u64 v[14:15], v[14:15], 0, v[38:39]
	s_mov_b64 s[4:5], 0x4d604000
	v_lshl_add_u64 v[14:15], v[14:15], 0, s[4:5]
	v_pk_mul_f32 v[16:17], v[30:31], v[12:13] op_sel_hi:[1,0]
	v_pk_mul_f32 v[18:19], v[6:7], v[12:13] op_sel_hi:[1,0]
	v_cvt_pk_bf16_f32 v16, v16, v17
	v_cvt_pk_bf16_f32 v17, v18, v19
	v_pk_mul_f32 v[18:19], v[10:11], v[12:13] op_sel_hi:[1,0]
	v_pk_mul_f32 v[12:13], v[8:9], v[12:13] op_sel_hi:[1,0]
	v_cvt_pk_bf16_f32 v18, v18, v19
	v_cvt_pk_bf16_f32 v19, v12, v13
	v_lshl_add_u64 v[12:13], v[14:15], 0, v[94:95]
	global_store_dwordx2 v[12:13], v[16:17], off nt
	v_lshl_add_u64 v[12:13], v[14:15], 0, v[96:97]
	global_store_dwordx2 v[12:13], v[18:19], off nt
	ds_read_b32 v12, v137
	v_lshl_add_u64 v[14:15], s[30:31], 0, v[98:99]
	v_lshl_add_u64 v[14:15], v[14:15], 0, v[38:39]
	s_mov_b64 s[4:5], 0x56604000
	v_lshl_add_u64 v[14:15], v[14:15], 0, s[4:5]
	s_waitcnt lgkmcnt(0)
	v_mul_f32_e32 v12, 0x3fb8aa3b, v12
	v_exp_f32_e32 v12, v12
	s_nop 0
	v_pk_mul_f32 v[16:17], v[30:31], v[12:13] op_sel_hi:[1,0]
	v_pk_mul_f32 v[6:7], v[6:7], v[12:13] op_sel_hi:[1,0]
	v_cvt_pk_bf16_f32 v16, v16, v17
	v_cvt_pk_bf16_f32 v17, v6, v7
	v_pk_mul_f32 v[6:7], v[10:11], v[12:13] op_sel_hi:[1,0]
	v_pk_mul_f32 v[8:9], v[8:9], v[12:13] op_sel_hi:[1,0]
	v_cvt_pk_bf16_f32 v6, v6, v7
	v_cvt_pk_bf16_f32 v7, v8, v9
	v_lshl_add_u64 v[8:9], v[14:15], 0, v[100:101]
	global_store_dwordx2 v[8:9], v[16:17], off nt
	v_lshl_add_u64 v[8:9], v[14:15], 0, v[102:103]
	global_store_dwordx2 v[8:9], v[6:7], off nt

; __device__ __forceinline__ unsigned cvtpk(float lo, float hi) { const f32x2_t v = {lo, hi}; const bf16x2_t b = __builtin_convertvector(v, bf16x2_t); return __builtin_bit_cast(unsigned, b); }
; __device__ __forceinline__ int crow(int r, int hi) { return (r & 3) + 8 * (r >> 2) + 4 * hi; }
; __device__ __forceinline__ void gdn_prep_unit(LAS unsigned char* lds, unsigned char* ws, const float* conv_w, const float* a_log, const float* dt_bias,
;                                               int l, int Tp, int ci, int h, int nci, int nh, unsigned& pre_ba, int tid, int wave, int lane) {
;     ...
;             } else {
;                 float v[16];
; #pragma unroll
;                 for (int r = 0; r < 16; ++r) { const int cp = 32 * ta + crow(r, hi);
;                     v[r] = (colp >= cp) ? acc[r] * __expf(gcc - GC[d * 64 + cp]) : 0.f; }
;                 unsigned char* fb = gdn_rec(ws, d, ci, h) + REC_FQK + (((tb * 2 + ta) * 2) * 64 + lane) * 16;
;                 v4u o0, o1; o0.x = cvtpk(v[0], v[1]); o0.y = cvtpk(v[2], v[3]); o0.z = cvtpk(v[4], v[5]); o0.w = cvtpk(v[6], v[7]);
;                 o1.x = cvtpk(v[8], v[9]); o1.y = cvtpk(v[10], v[11]); o1.z = cvtpk(v[12], v[13]); o1.w = cvtpk(v[14], v[15]);
;                 *(v4u*)fb = o0; *(v4u*)(fb + 1024) = o1;
.LBB0_448:
	s_or_b64 exec, exec, s[30:31]
	s_ashr_i32 s85, s84, 31
	s_lshl_b64 s[4:5], s[84:85], 11
	s_add_u32 s4, s4, s7
	s_addc_u32 s5, s5, s81
	s_mul_i32 s5, s5, 0x12000
	s_mul_hi_u32 s17, s4, 0x12000
	s_add_i32 s17, s17, s5
	s_mul_i32 s4, s4, 0x12000
	s_add_u32 s4, s42, s4
	s_addc_u32 s5, s43, s17
	s_and_b64 s[18:19], s[88:89], exec
	v_cndmask_b32_e64 v27, 0, 1, s[26:27]
	s_cselect_b32 s17, 2, 0
	v_or_b32_e32 v27, s17, v27
	v_lshl_or_b32 v196, v27, 11, v145
	v_mov_b32_e32 v197, v4
	v_lshl_add_u64 v[196:197], s[4:5], 0, v[196:197]
	v_cvt_pk_bf16_f32 v27, v29, v28
	v_cvt_pk_bf16_f32 v28, v31, v30
	v_cvt_pk_bf16_f32 v30, v35, v34
	v_add_co_u32_e32 v34, vcc, 0x4d60c000, v196
	s_mov_b64 s[4:5], 0x4d60c000
	v_cvt_pk_bf16_f32 v26, v26, v25
	v_cvt_pk_bf16_f32 v29, v33, v32
	v_addc_co_u32_e32 v35, vcc, 0, v197, vcc
	v_lshl_add_u64 v[216:217], v[196:197], 0, s[4:5]
	v_cvt_pk_bf16_f32 v31, v37, v36
	v_cvt_pk_bf16_f32 v32, v212, v211
	v_cvt_pk_bf16_f32 v33, v214, v213
	global_store_dwordx4 v[34:35], v[26:29], off nt
	global_store_dwordx4 v[216:217], v[30:33], off offset:1024 nt
	s_mov_b32 s31, s52
	s_branch .LBB0_413

; __device__ __forceinline__ float bflo(unsigned w) { return __uint_as_float(w << 16); }
; __device__ __forceinline__ float bfhi(unsigned w) { return __uint_as_float(w & 0xffff0000u); }
; #define LAS __attribute__((address_space(3)))
; __device__ __forceinline__ float bflo(unsigned w) { return __uint_as_float(w << 16); }
; __device__ __forceinline__ float bfhi(unsigned w) { return __uint_as_float(w & 0xffff0000u); }
; __device__ __forceinline__ unsigned cvtpk(float lo, float hi) { const f32x2_t v = {lo, hi}; const bf16x2_t b = __builtin_convertvector(v, bf16x2_t); return __builtin_bit_cast(unsigned, b); }
; __device__ __forceinline__ void gdn_prep_unit(LAS unsigned char* lds, unsigned char* ws, const float* conv_w, const float* a_log, const float* dt_bias,
;                                               int l, int Tp, int ci, int h, int nci, int nh, unsigned& pre_ba, int tid, int wave, int lane) {
;     ...
;             const float gl = GC[d * 64 + 63];
;             const int ktr = 32 * t + rr; const LAS unsigned char* kt = lds + D1_KT;
;             float ea[4], eb[4];
; #pragma unroll
;             for (int x = 0; x < 4; ++x) { ea[x] = __expf(gl - GC[d * 64 + c0 + x]); eb[x] = __expf(gl - GC[d * 64 + c0 + 8 + x]); }
;             float ka[4], kb[4];
;             if (d == 0) { const v2u wa = *(const LAS v2u*)(kt + TSW(ktr, c0 * 2)), wb = *(const LAS v2u*)(kt + TSW(ktr, (c0 + 8) * 2));
;                 ka[0] = bflo(wa.x); ka[1] = bfhi(wa.x); ka[2] = bflo(wa.y); ka[3] = bfhi(wa.y); kb[0] = bflo(wb.x); kb[1] = bfhi(wb.x); kb[2] = bflo(wb.y); kb[3] = bfhi(wb.y); }
;             else { const v2u wa = *(const LAS v2u*)(kt + TSW(ktr, (60 - c0) * 2)), wb = *(const LAS v2u*)(kt + TSW(ktr, (52 - c0) * 2));
;                 ka[3] = bflo(wa.x); ka[2] = bfhi(wa.x); ka[1] = bflo(wa.y); ka[0] = bfhi(wa.y); kb[3] = bflo(wb.x); kb[2] = bfhi(wb.x); kb[1] = bflo(wb.y); kb[0] = bfhi(wb.y); }
;             v4u o; o.x = cvtpk(ka[0] * ea[0], ka[1] * ea[1]); o.y = cvtpk(ka[2] * ea[2], ka[3] * ea[3]); o.z = cvtpk(kb[0] * eb[0], kb[1] * eb[1]); o.w = cvtpk(kb[2] * eb[2], kb[3] * eb[3]);
;             *(v4u*)(gdn_rec(ws, d, ci, h) + REC_FK + (((t * 2 + ip) * 2 + s) * 64 + lane) * 16) = o;
.LBB0_494:
	s_waitcnt lgkmcnt(0)
	v_sub_f32_e32 v6, v14, v6
	v_sub_f32_e32 v7, v14, v7
	v_sub_f32_e32 v8, v14, v8
	v_mul_f32_e32 v6, 0x3fb8aa3b, v6
	v_mul_f32_e32 v7, 0x3fb8aa3b, v7
	v_mul_f32_e32 v8, 0x3fb8aa3b, v8
	v_sub_f32_e32 v10, v14, v10
	v_exp_f32_e32 v23, v6
	v_sub_f32_e32 v6, v14, v11
	v_exp_f32_e32 v11, v7
	v_sub_f32_e32 v7, v14, v12
	v_exp_f32_e32 v12, v8
	v_sub_f32_e32 v8, v14, v13
	v_mul_f32_e32 v10, 0x3fb8aa3b, v10
	v_mul_f32_e32 v6, 0x3fb8aa3b, v6
	v_mul_f32_e32 v7, 0x3fb8aa3b, v7
	v_mul_f32_e32 v8, 0x3fb8aa3b, v8
	v_exp_f32_e32 v10, v10
	v_exp_f32_e32 v6, v6
	v_exp_f32_e32 v7, v7
	v_exp_f32_e32 v8, v8
	v_sub_f32_e32 v9, v14, v9
	v_mul_f32_e32 v9, 0x3fb8aa3b, v9
	s_lshl_b64 s[4:5], s[60:61], 11
	v_exp_f32_e32 v9, v9
	s_add_u32 s4, s4, s7
	s_addc_u32 s5, s5, s81
	v_mul_f32_e32 v10, v10, v22
	v_mul_f32_e32 v6, v6, v21
	v_mul_f32_e32 v7, v7, v20
	v_mul_f32_e32 v8, v8, v19
	s_mul_i32 s5, s5, 0x12000
	s_mul_hi_u32 s19, s4, 0x12000
	v_cvt_pk_bf16_f32 v6, v10, v6
	v_cvt_pk_bf16_f32 v7, v7, v8
	v_mul_f32_e32 v8, v23, v18
	v_mul_f32_e32 v10, v11, v17
	s_add_i32 s19, s19, s5
	s_mul_i32 s4, s4, 0x12000
	v_cvt_pk_bf16_f32 v8, v8, v10
	v_mul_f32_e32 v10, v12, v16
	v_mul_f32_e32 v9, v9, v15
	s_add_u32 s4, s42, s4
	v_cvt_pk_bf16_f32 v9, v10, v9
	s_addc_u32 s5, s43, s19
	v_lshl_or_b32 v10, s18, 12, v203
	v_mov_b32_e32 v11, v4
	v_lshl_add_u64 v[10:11], s[4:5], 0, v[10:11]
	v_add_co_u32_e32 v10, vcc, 0x4d608000, v10
	s_add_i32 s16, s16, 1
	s_nop 0
	v_addc_co_u32_e32 v11, vcc, 0, v11, vcc
	s_cmp_lt_i32 s17, 28
	global_store_dwordx4 v[10:11], v[6:9], off nt
	s_cbranch_scc0 .LBB0_483

; __device__ __forceinline__ unsigned cvtpk(float lo, float hi) { const f32x2_t v = {lo, hi}; const bf16x2_t b = __builtin_convertvector(v, bf16x2_t); return __builtin_bit_cast(unsigned, b); }
; __device__ __forceinline__ void gdn_prep_unit(LAS unsigned char* lds, unsigned char* ws, const float* conv_w, const float* a_log, const float* dt_bias,
;                                               int l, int Tp, int ci, int h, int nci, int nh, unsigned& pre_ba, int tid, int wave, int lane) {
;     ...
;             const float sg = kind ? -1.f : 1.f;
;             v4u o0, o1; o0.x = cvtpk(sg * acc[0], sg * acc[1]); o0.y = cvtpk(sg * acc[2], sg * acc[3]); o0.z = cvtpk(sg * acc[4], sg * acc[5]); o0.w = cvtpk(sg * acc[6], sg * acc[7]);
;             o1.x = cvtpk(sg * acc[8], sg * acc[9]); o1.y = cvtpk(sg * acc[10], sg * acc[11]); o1.z = cvtpk(sg * acc[12], sg * acc[13]); o1.w = cvtpk(sg * acc[14], sg * acc[15]);
;             if (kind == 0) { const int i = idx >> 2, w = idx & 3; unsigned char* fb = gdn_rec(ws, d, ci, h) + REC_FU + ((w * 2 + i) * 64 + lane) * 32; *(v4u*)fb = o0; *(v4u*)(fb + 16) = o1; }
;             else { const int t = idx >> 1, i = idx & 1; unsigned char* fb = gdn_rec(ws, d, ci, h) + REC_FW + (((i * 4 + t) * 2) * 64 + lane) * 16; *(v4u*)fb = o0; *(v4u*)(fb + 1024) = o1; }
.LBB0_500:
	v_pk_mul_f32 v[6:7], s[26:27], v[6:7] op_sel_hi:[0,1]
	s_nop 1
	v_pk_mul_f32 v[8:9], s[26:27], v[8:9] op_sel_hi:[0,1]
	s_lshl_b32 s4, s17, s29
	v_cvt_pk_bf16_f32 v6, v6, v7
	v_cvt_pk_bf16_f32 v7, v8, v9
	v_pk_mul_f32 v[8:9], s[26:27], v[10:11] op_sel_hi:[0,1]
	v_pk_mul_f32 v[10:11], s[26:27], v[12:13] op_sel_hi:[0,1]
	s_and_b32 s4, s4, s27
	v_cvt_pk_bf16_f32 v8, v8, v9
	v_cvt_pk_bf16_f32 v9, v10, v11
	v_pk_mul_f32 v[10:11], s[26:27], v[14:15] op_sel_hi:[0,1]
	v_pk_mul_f32 v[12:13], s[26:27], v[16:17] op_sel_hi:[0,1]
	s_add_i32 s4, s4, s18
	v_cvt_pk_bf16_f32 v10, v10, v11
	v_cvt_pk_bf16_f32 v11, v12, v13
	v_pk_mul_f32 v[12:13], s[26:27], v[18:19] op_sel_hi:[0,1]
	v_pk_mul_f32 v[14:15], s[26:27], v[20:21] op_sel_hi:[0,1]
	s_lshl_b32 s4, s4, s19
	v_cvt_pk_bf16_f32 v12, v12, v13
	v_cvt_pk_bf16_f32 v13, v14, v15
	v_add_u32_e32 v14, s4, v22
	v_mov_b32_e32 v15, v4
	v_lshl_add_u64 v[16:17], s[84:85], 0, v[14:15]
	s_add_i32 s4, s17, 8
	s_addk_i32 s16, 0x100
	global_store_dwordx4 v14, v[6:9], s[84:85] nt
	s_cmp_lt_i32 s17, 24
	s_mov_b32 s17, s4
	v_lshl_add_u64 v[6:7], v[16:17], 0, s[30:31]
	global_store_dwordx4 v[6:7], v[10:13], off nt
	s_cbranch_scc0 .LBB0_318
